# attention epilogue: the four output-gate loads of each query block issued together (were serialized behind stores)
# baseline (speedup 1.0000x reference)
.LBB0_827:
	s_or_b64 exec, exec, s[34:35]
	ds_bpermute_b32 v20, v160, v136
	s_movk_i32 s0, 0xef
	v_cmp_lt_i32_e64 s[6:7], s0, v164
	s_waitcnt lgkmcnt(0)
	v_add_f32_e32 v22, v136, v20
	ds_bpermute_b32 v23, v161, v22
	v_or_b32_e32 v20, v138, v158
	v_ashrrev_i32_e32 v21, 31, v20
	s_and_saveexec_b64 s[8:9], s[6:7]
	s_cbranch_execz .LBB0_829
	v_add_u32_e32 v172, 0xffffff10, v164
	v_lshl_add_u64 v[24:25], v[134:135], 0, v[172:173]
	v_lshlrev_b64 v[26:27], 12, v[24:25]
	v_lshl_add_u64 v[26:27], s[54:55], 0, v[26:27]
	v_lshlrev_b64 v[28:29], 1, v[20:21]
	v_lshl_add_u64 v[26:27], v[26:27], 0, v[28:29]
	global_load_dwordx2 v[30:31], v[26:27], off offset:2048
	v_lshlrev_b64 v[24:25], 11, v[24:25]
	v_lshl_add_u64 v[24:25], s[44:45], 0, v[24:25]
	v_lshl_add_u64 v[24:25], v[24:25], 0, v[28:29]
	global_load_dwordx2 v[28:29], v[26:27], off offset:2080
	global_load_dwordx2 v[72:73], v[26:27], off offset:2112
	global_load_dwordx2 v[74:75], v[26:27], off offset:2144
	s_waitcnt lgkmcnt(0)
	v_add_f32_e32 v22, v22, v23
	v_rcp_f32_e32 v22, v22
	v_mov_b32_e32 v34, v68
	v_mov_b32_e32 v35, v70
	v_mov_b32_e32 v70, v69
	s_waitcnt vmcnt(3)
	v_lshlrev_b32_e32 v23, 16, v30
	v_mul_f32_e32 v23, 0xbfb8aa3b, v23
	v_exp_f32_e32 v23, v23
	s_nop 0
	v_add_f32_e32 v23, 1.0, v23
	v_rcp_f32_e32 v32, v23
	v_and_b32_e32 v23, 0xffff0000, v30
	v_mul_f32_e32 v23, 0xbfb8aa3b, v23
	v_exp_f32_e32 v23, v23
	s_nop 0
	v_add_f32_e32 v23, 1.0, v23
	v_rcp_f32_e32 v30, v23
	v_lshlrev_b32_e32 v23, 16, v31
	v_mul_f32_e32 v23, 0xbfb8aa3b, v23
	v_exp_f32_e32 v23, v23
	s_nop 0
	v_add_f32_e32 v23, 1.0, v23
	v_rcp_f32_e32 v33, v23
	v_and_b32_e32 v23, 0xffff0000, v31
	v_mul_f32_e32 v23, 0xbfb8aa3b, v23
	v_exp_f32_e32 v23, v23
	s_nop 0
	v_add_f32_e32 v23, 1.0, v23
	v_rcp_f32_e32 v31, v23
	v_pk_mul_f32 v[34:35], v[34:35], v[22:23] op_sel_hi:[1,0]
	s_nop 0
	v_pk_mul_f32 v[32:33], v[34:35], v[32:33]
	v_pk_mul_f32 v[34:35], v[70:71], v[22:23] op_sel_hi:[1,0]
	v_and_b32_sdwa v23, v33, v196 dst_sel:DWORD dst_unused:UNUSED_PAD src0_sel:WORD_1 src1_sel:DWORD
	v_pk_mul_f32 v[30:31], v[34:35], v[30:31]
	v_add3_u32 v23, v33, v23, s96
	v_and_b32_sdwa v33, v31, v196 dst_sel:DWORD dst_unused:UNUSED_PAD src0_sel:WORD_1 src1_sel:DWORD
	v_add3_u32 v31, v31, v33, s96
	v_and_b32_e32 v31, 0xffff0000, v31
	v_or_b32_sdwa v31, v31, v23 dst_sel:DWORD dst_unused:UNUSED_PAD src0_sel:DWORD src1_sel:WORD_1
	s_waitcnt vmcnt(2)
	v_lshlrev_b32_e32 v23, 16, v28
	v_mul_f32_e32 v23, 0xbfb8aa3b, v23
	v_and_b32_sdwa v34, v32, v196 dst_sel:DWORD dst_unused:UNUSED_PAD src0_sel:WORD_1 src1_sel:DWORD
	v_exp_f32_e32 v23, v23
	v_add3_u32 v32, v32, v34, s96
	v_and_b32_sdwa v34, v30, v196 dst_sel:DWORD dst_unused:UNUSED_PAD src0_sel:WORD_1 src1_sel:DWORD
	v_add3_u32 v30, v30, v34, s96
	v_and_b32_e32 v30, 0xffff0000, v30
	v_or_b32_sdwa v30, v30, v32 dst_sel:DWORD dst_unused:UNUSED_PAD src0_sel:DWORD src1_sel:WORD_1
	v_add_f32_e32 v23, 1.0, v23
	global_store_dwordx2 v[24:25], v[30:31], off
	v_rcp_f32_e32 v30, v23
	v_and_b32_e32 v23, 0xffff0000, v28
	v_mul_f32_e32 v23, 0xbfb8aa3b, v23
	v_exp_f32_e32 v23, v23
	v_mov_b32_e32 v32, v64
	v_mov_b32_e32 v33, v66
	v_mov_b32_e32 v66, v65
	v_add_f32_e32 v23, 1.0, v23
	v_rcp_f32_e32 v28, v23
	v_lshlrev_b32_e32 v23, 16, v29
	v_mul_f32_e32 v23, 0xbfb8aa3b, v23
	v_exp_f32_e32 v23, v23
	s_nop 0
	v_add_f32_e32 v23, 1.0, v23
	v_rcp_f32_e32 v31, v23
	v_and_b32_e32 v23, 0xffff0000, v29
	v_mul_f32_e32 v23, 0xbfb8aa3b, v23
	v_exp_f32_e32 v23, v23
	s_nop 0
	v_add_f32_e32 v23, 1.0, v23
	v_rcp_f32_e32 v29, v23
	v_pk_mul_f32 v[32:33], v[32:33], v[22:23] op_sel_hi:[1,0]
	s_nop 0
	v_pk_mul_f32 v[30:31], v[32:33], v[30:31]
	v_pk_mul_f32 v[32:33], v[66:67], v[22:23] op_sel_hi:[1,0]
	v_and_b32_sdwa v23, v31, v196 dst_sel:DWORD dst_unused:UNUSED_PAD src0_sel:WORD_1 src1_sel:DWORD
	v_pk_mul_f32 v[28:29], v[32:33], v[28:29]
	v_and_b32_sdwa v32, v30, v196 dst_sel:DWORD dst_unused:UNUSED_PAD src0_sel:WORD_1 src1_sel:DWORD
	v_add3_u32 v30, v30, v32, s96
	v_add3_u32 v23, v31, v23, s96
	v_and_b32_sdwa v31, v29, v196 dst_sel:DWORD dst_unused:UNUSED_PAD src0_sel:WORD_1 src1_sel:DWORD
	v_and_b32_sdwa v32, v28, v196 dst_sel:DWORD dst_unused:UNUSED_PAD src0_sel:WORD_1 src1_sel:DWORD
	v_add3_u32 v29, v29, v31, s96
	v_add3_u32 v28, v28, v32, s96
	v_and_b32_e32 v29, 0xffff0000, v29
	v_and_b32_e32 v28, 0xffff0000, v28
	v_or_b32_sdwa v29, v29, v23 dst_sel:DWORD dst_unused:UNUSED_PAD src0_sel:DWORD src1_sel:WORD_1
	v_or_b32_sdwa v28, v28, v30 dst_sel:DWORD dst_unused:UNUSED_PAD src0_sel:DWORD src1_sel:WORD_1
	global_store_dwordx2 v[24:25], v[28:29], off offset:32
	v_mov_b32_e32 v32, v60
	v_mov_b32_e32 v33, v62
	v_mov_b32_e32 v62, v61
	s_waitcnt vmcnt(3)
	v_lshlrev_b32_e32 v23, 16, v72
	v_mul_f32_e32 v23, 0xbfb8aa3b, v23
	v_exp_f32_e32 v23, v23
	s_nop 0
	v_add_f32_e32 v23, 1.0, v23
	v_rcp_f32_e32 v30, v23
	v_and_b32_e32 v23, 0xffff0000, v72
	v_mul_f32_e32 v23, 0xbfb8aa3b, v23
	v_exp_f32_e32 v23, v23
	s_nop 0
	v_add_f32_e32 v23, 1.0, v23
	v_rcp_f32_e32 v28, v23
	v_lshlrev_b32_e32 v23, 16, v73
	v_mul_f32_e32 v23, 0xbfb8aa3b, v23
	v_exp_f32_e32 v23, v23
	s_nop 0
	v_add_f32_e32 v23, 1.0, v23
	v_rcp_f32_e32 v31, v23
	v_and_b32_e32 v23, 0xffff0000, v73
	v_mul_f32_e32 v23, 0xbfb8aa3b, v23
	v_exp_f32_e32 v23, v23
	s_nop 0
	v_add_f32_e32 v23, 1.0, v23
	v_rcp_f32_e32 v29, v23
	v_pk_mul_f32 v[32:33], v[32:33], v[22:23] op_sel_hi:[1,0]
	s_nop 0
	v_pk_mul_f32 v[30:31], v[32:33], v[30:31]
	v_pk_mul_f32 v[32:33], v[62:63], v[22:23] op_sel_hi:[1,0]
	v_and_b32_sdwa v23, v31, v196 dst_sel:DWORD dst_unused:UNUSED_PAD src0_sel:WORD_1 src1_sel:DWORD
	v_pk_mul_f32 v[28:29], v[32:33], v[28:29]
	v_add3_u32 v23, v31, v23, s96
	v_and_b32_sdwa v31, v29, v196 dst_sel:DWORD dst_unused:UNUSED_PAD src0_sel:WORD_1 src1_sel:DWORD
	v_add3_u32 v29, v29, v31, s96
	v_and_b32_e32 v29, 0xffff0000, v29
	v_or_b32_sdwa v29, v29, v23 dst_sel:DWORD dst_unused:UNUSED_PAD src0_sel:DWORD src1_sel:WORD_1
	s_waitcnt vmcnt(2)
	v_lshlrev_b32_e32 v23, 16, v74
	v_mul_f32_e32 v23, 0xbfb8aa3b, v23
	v_and_b32_sdwa v32, v30, v196 dst_sel:DWORD dst_unused:UNUSED_PAD src0_sel:WORD_1 src1_sel:DWORD
	v_exp_f32_e32 v23, v23
	v_add3_u32 v30, v30, v32, s96
	v_and_b32_sdwa v32, v28, v196 dst_sel:DWORD dst_unused:UNUSED_PAD src0_sel:WORD_1 src1_sel:DWORD
	v_add3_u32 v28, v28, v32, s96
	v_and_b32_e32 v28, 0xffff0000, v28
	v_or_b32_sdwa v28, v28, v30 dst_sel:DWORD dst_unused:UNUSED_PAD src0_sel:DWORD src1_sel:WORD_1
	v_add_f32_e32 v23, 1.0, v23
	global_store_dwordx2 v[24:25], v[28:29], off offset:64
	v_rcp_f32_e32 v28, v23
	v_and_b32_e32 v23, 0xffff0000, v74
	v_mul_f32_e32 v23, 0xbfb8aa3b, v23
	v_exp_f32_e32 v23, v23
	v_mov_b32_e32 v31, v18
	v_mov_b32_e32 v18, v17
	v_mov_b32_e32 v30, v16
	v_add_f32_e32 v23, 1.0, v23
	v_rcp_f32_e32 v26, v23
	v_lshlrev_b32_e32 v23, 16, v75
	v_mul_f32_e32 v23, 0xbfb8aa3b, v23
	v_exp_f32_e32 v23, v23
	s_nop 0
	v_add_f32_e32 v23, 1.0, v23
	v_rcp_f32_e32 v29, v23
	v_and_b32_e32 v23, 0xffff0000, v75
	v_mul_f32_e32 v23, 0xbfb8aa3b, v23
	v_exp_f32_e32 v23, v23
	s_nop 0
	v_add_f32_e32 v23, 1.0, v23
	v_rcp_f32_e32 v27, v23
	v_pk_mul_f32 v[16:17], v[18:19], v[22:23] op_sel_hi:[1,0]
	v_pk_mul_f32 v[30:31], v[30:31], v[22:23] op_sel_hi:[1,0]
	v_pk_mul_f32 v[16:17], v[16:17], v[26:27]
	v_pk_mul_f32 v[28:29], v[30:31], v[28:29]
	v_and_b32_sdwa v22, v17, v196 dst_sel:DWORD dst_unused:UNUSED_PAD src0_sel:WORD_1 src1_sel:DWORD
	v_and_b32_sdwa v23, v16, v196 dst_sel:DWORD dst_unused:UNUSED_PAD src0_sel:WORD_1 src1_sel:DWORD
	v_and_b32_sdwa v18, v29, v196 dst_sel:DWORD dst_unused:UNUSED_PAD src0_sel:WORD_1 src1_sel:DWORD
	v_and_b32_sdwa v19, v28, v196 dst_sel:DWORD dst_unused:UNUSED_PAD src0_sel:WORD_1 src1_sel:DWORD
	v_add3_u32 v17, v17, v22, s96
	v_add3_u32 v16, v16, v23, s96
	v_add3_u32 v19, v28, v19, s96
	v_add3_u32 v18, v29, v18, s96
	v_and_b32_e32 v17, 0xffff0000, v17
	v_and_b32_e32 v16, 0xffff0000, v16
	v_or_b32_sdwa v17, v17, v18 dst_sel:DWORD dst_unused:UNUSED_PAD src0_sel:DWORD src1_sel:WORD_1
	v_or_b32_sdwa v16, v16, v19 dst_sel:DWORD dst_unused:UNUSED_PAD src0_sel:DWORD src1_sel:WORD_1
	global_store_dwordx2 v[24:25], v[16:17], off offset:96
.LBB0_829:
	s_or_b64 exec, exec, s[8:9]
	ds_bpermute_b32 v16, v160, v137
	v_cmp_lt_i32_e64 s[6:7], s0, v139
	s_waitcnt lgkmcnt(0)
	v_add_f32_e32 v16, v137, v16
	ds_bpermute_b32 v17, v161, v16
	s_and_saveexec_b64 s[8:9], s[6:7]
	s_xor_b64 s[6:7], exec, s[8:9]
	s_movk_i32 s73, 0x4000
	s_mov_b32 s76, 0x3f317217
	s_mov_b32 s77, 0x7f800000
	s_movk_i32 s84, 0x407f
	s_mov_b32 s87, s60
	s_cbranch_execz .LBB0_788
	v_add_u32_e32 v172, 0xffffff20, v164
	v_lshl_add_u64 v[18:19], v[134:135], 0, v[172:173]
	v_lshlrev_b64 v[22:23], 12, v[18:19]
	v_lshl_add_u64 v[22:23], s[54:55], 0, v[22:23]
	v_lshlrev_b64 v[18:19], 11, v[18:19]
	v_lshlrev_b64 v[20:21], 1, v[20:21]
	v_lshl_add_u64 v[24:25], s[44:45], 0, v[18:19]
	v_lshl_add_u64 v[18:19], v[22:23], 0, v[20:21]
	global_load_dwordx2 v[22:23], v[18:19], off offset:2048
	global_load_dwordx2 v[76:77], v[18:19], off offset:2080
	global_load_dwordx2 v[78:79], v[18:19], off offset:2112
	global_load_dwordx2 v[80:81], v[18:19], off offset:2144
	s_waitcnt lgkmcnt(0)
	v_add_f32_e32 v16, v16, v17
	v_rcp_f32_e32 v16, v16
	v_mov_b32_e32 v28, v12
	v_mov_b32_e32 v29, v14
	v_mov_b32_e32 v14, v13
	s_waitcnt vmcnt(3)
	v_lshlrev_b32_e32 v17, 16, v22
	v_mul_f32_e32 v17, 0xbfb8aa3b, v17
	v_exp_f32_e32 v17, v17
	s_nop 0
	v_add_f32_e32 v17, 1.0, v17
	v_rcp_f32_e32 v26, v17
	v_and_b32_e32 v17, 0xffff0000, v22
	v_mul_f32_e32 v17, 0xbfb8aa3b, v17
	v_exp_f32_e32 v17, v17
	s_nop 0
	v_add_f32_e32 v17, 1.0, v17
	v_rcp_f32_e32 v22, v17
	v_lshlrev_b32_e32 v17, 16, v23
	v_mul_f32_e32 v17, 0xbfb8aa3b, v17
	v_exp_f32_e32 v17, v17
	s_nop 0
	v_add_f32_e32 v17, 1.0, v17
	v_rcp_f32_e32 v27, v17
	v_and_b32_e32 v17, 0xffff0000, v23
	v_mul_f32_e32 v17, 0xbfb8aa3b, v17
	v_exp_f32_e32 v17, v17
	s_nop 0
	v_add_f32_e32 v17, 1.0, v17
	v_rcp_f32_e32 v23, v17
	v_pk_mul_f32 v[28:29], v[28:29], v[16:17] op_sel_hi:[1,0]
	v_pk_mul_f32 v[12:13], v[14:15], v[16:17] op_sel_hi:[1,0]
	v_pk_mul_f32 v[26:27], v[28:29], v[26:27]
	v_pk_mul_f32 v[12:13], v[12:13], v[22:23]
	v_and_b32_sdwa v15, v26, v196 dst_sel:DWORD dst_unused:UNUSED_PAD src0_sel:WORD_1 src1_sel:DWORD
	v_add3_u32 v17, v26, v15, s96
	v_and_b32_sdwa v15, v13, v196 dst_sel:DWORD dst_unused:UNUSED_PAD src0_sel:WORD_1 src1_sel:DWORD
	v_and_b32_sdwa v22, v12, v196 dst_sel:DWORD dst_unused:UNUSED_PAD src0_sel:WORD_1 src1_sel:DWORD
	v_and_b32_sdwa v14, v27, v196 dst_sel:DWORD dst_unused:UNUSED_PAD src0_sel:WORD_1 src1_sel:DWORD
	v_add3_u32 v13, v13, v15, s96
	v_add3_u32 v12, v12, v22, s96
	v_add3_u32 v14, v27, v14, s96
	v_and_b32_e32 v13, 0xffff0000, v13
	v_and_b32_e32 v12, 0xffff0000, v12
	v_or_b32_sdwa v15, v13, v14 dst_sel:DWORD dst_unused:UNUSED_PAD src0_sel:DWORD src1_sel:WORD_1
	v_or_b32_sdwa v14, v12, v17 dst_sel:DWORD dst_unused:UNUSED_PAD src0_sel:DWORD src1_sel:WORD_1
	v_lshl_add_u64 v[12:13], v[24:25], 0, v[20:21]
	global_store_dwordx2 v[12:13], v[14:15], off
	v_mov_b32_e32 v23, v10
	v_mov_b32_e32 v10, v9
	v_mov_b32_e32 v22, v8
	s_waitcnt vmcnt(3)
	v_lshlrev_b32_e32 v17, 16, v76
	v_mul_f32_e32 v17, 0xbfb8aa3b, v17
	v_exp_f32_e32 v17, v17
	v_and_b32_e32 v14, 0xffff0000, v76
	v_mul_f32_e32 v14, 0xbfb8aa3b, v14
	v_exp_f32_e32 v14, v14
	v_add_f32_e32 v17, 1.0, v17
	v_rcp_f32_e32 v20, v17
	v_lshlrev_b32_e32 v17, 16, v77
	v_and_b32_e32 v15, 0xffff0000, v77
	v_mul_f32_e32 v15, 0xbfb8aa3b, v15
	v_mul_f32_e32 v17, 0xbfb8aa3b, v17
	v_exp_f32_e32 v15, v15
	v_exp_f32_e32 v17, v17
	v_add_f32_e32 v14, 1.0, v14
	v_rcp_f32_e32 v14, v14
	v_add_f32_e32 v15, 1.0, v15
	v_add_f32_e32 v17, 1.0, v17
	v_rcp_f32_e32 v15, v15
	v_rcp_f32_e32 v21, v17
	v_pk_mul_f32 v[8:9], v[10:11], v[16:17] op_sel_hi:[1,0]
	v_pk_mul_f32 v[22:23], v[22:23], v[16:17] op_sel_hi:[1,0]
	v_pk_mul_f32 v[8:9], v[8:9], v[14:15]
	v_pk_mul_f32 v[20:21], v[22:23], v[20:21]
	v_and_b32_sdwa v14, v9, v196 dst_sel:DWORD dst_unused:UNUSED_PAD src0_sel:WORD_1 src1_sel:DWORD
	v_and_b32_sdwa v15, v8, v196 dst_sel:DWORD dst_unused:UNUSED_PAD src0_sel:WORD_1 src1_sel:DWORD
	v_and_b32_sdwa v10, v21, v196 dst_sel:DWORD dst_unused:UNUSED_PAD src0_sel:WORD_1 src1_sel:DWORD
	v_and_b32_sdwa v11, v20, v196 dst_sel:DWORD dst_unused:UNUSED_PAD src0_sel:WORD_1 src1_sel:DWORD
	v_add3_u32 v9, v9, v14, s96
	v_add3_u32 v8, v8, v15, s96
	v_add3_u32 v11, v20, v11, s96
	v_add3_u32 v10, v21, v10, s96
	v_and_b32_e32 v9, 0xffff0000, v9
	v_and_b32_e32 v8, 0xffff0000, v8
	v_or_b32_sdwa v9, v9, v10 dst_sel:DWORD dst_unused:UNUSED_PAD src0_sel:DWORD src1_sel:WORD_1
	v_or_b32_sdwa v8, v8, v11 dst_sel:DWORD dst_unused:UNUSED_PAD src0_sel:DWORD src1_sel:WORD_1
	global_store_dwordx2 v[12:13], v[8:9], off offset:32
	v_mov_b32_e32 v15, v6
	v_mov_b32_e32 v6, v5
	v_mov_b32_e32 v14, v4
	v_pk_mul_f32 v[4:5], v[6:7], v[16:17] op_sel_hi:[1,0]
	v_pk_mul_f32 v[14:15], v[14:15], v[16:17] op_sel_hi:[1,0]
	s_waitcnt vmcnt(3)
	v_lshlrev_b32_e32 v10, 16, v78
	v_and_b32_e32 v8, 0xffff0000, v78
	v_lshlrev_b32_e32 v11, 16, v79
	v_and_b32_e32 v9, 0xffff0000, v79
	v_mul_f32_e32 v8, 0xbfb8aa3b, v8
	v_mul_f32_e32 v9, 0xbfb8aa3b, v9
	v_mul_f32_e32 v10, 0xbfb8aa3b, v10
	v_exp_f32_e32 v8, v8
	v_mul_f32_e32 v11, 0xbfb8aa3b, v11
	v_exp_f32_e32 v9, v9
	v_exp_f32_e32 v10, v10
	v_exp_f32_e32 v11, v11
	v_add_f32_e32 v8, 1.0, v8
	v_add_f32_e32 v9, 1.0, v9
	v_add_f32_e32 v10, 1.0, v10
	v_rcp_f32_e32 v8, v8
	v_add_f32_e32 v11, 1.0, v11
	v_rcp_f32_e32 v9, v9
	v_rcp_f32_e32 v10, v10
	v_rcp_f32_e32 v11, v11
	v_pk_mul_f32 v[4:5], v[4:5], v[8:9]
	s_nop 0
	v_and_b32_sdwa v8, v5, v196 dst_sel:DWORD dst_unused:UNUSED_PAD src0_sel:WORD_1 src1_sel:DWORD
	v_pk_mul_f32 v[10:11], v[14:15], v[10:11]
	v_and_b32_sdwa v9, v4, v196 dst_sel:DWORD dst_unused:UNUSED_PAD src0_sel:WORD_1 src1_sel:DWORD
	v_and_b32_sdwa v6, v11, v196 dst_sel:DWORD dst_unused:UNUSED_PAD src0_sel:WORD_1 src1_sel:DWORD
	v_and_b32_sdwa v7, v10, v196 dst_sel:DWORD dst_unused:UNUSED_PAD src0_sel:WORD_1 src1_sel:DWORD
	v_add3_u32 v5, v5, v8, s96
	v_add3_u32 v4, v4, v9, s96
	v_add3_u32 v7, v10, v7, s96
	v_add3_u32 v6, v11, v6, s96
	v_and_b32_e32 v5, 0xffff0000, v5
	v_and_b32_e32 v4, 0xffff0000, v4
	v_or_b32_sdwa v5, v5, v6 dst_sel:DWORD dst_unused:UNUSED_PAD src0_sel:DWORD src1_sel:WORD_1
	v_or_b32_sdwa v4, v4, v7 dst_sel:DWORD dst_unused:UNUSED_PAD src0_sel:DWORD src1_sel:WORD_1
	global_store_dwordx2 v[12:13], v[4:5], off offset:64
	v_mov_b32_e32 v9, v2
	v_mov_b32_e32 v2, v1
	v_mov_b32_e32 v8, v0
	v_pk_mul_f32 v[0:1], v[2:3], v[16:17] op_sel_hi:[1,0]
	v_pk_mul_f32 v[8:9], v[8:9], v[16:17] op_sel_hi:[1,0]
	s_waitcnt vmcnt(3)
	v_lshlrev_b32_e32 v6, 16, v80
	v_and_b32_e32 v4, 0xffff0000, v80
	v_lshlrev_b32_e32 v7, 16, v81
	v_and_b32_e32 v5, 0xffff0000, v81
	v_mul_f32_e32 v4, 0xbfb8aa3b, v4
	v_mul_f32_e32 v5, 0xbfb8aa3b, v5
	v_mul_f32_e32 v6, 0xbfb8aa3b, v6
	v_exp_f32_e32 v4, v4
	v_mul_f32_e32 v7, 0xbfb8aa3b, v7
	v_exp_f32_e32 v5, v5
	v_exp_f32_e32 v6, v6
	v_exp_f32_e32 v7, v7
	v_add_f32_e32 v4, 1.0, v4
	v_add_f32_e32 v5, 1.0, v5
	v_add_f32_e32 v6, 1.0, v6
	v_rcp_f32_e32 v4, v4
	v_add_f32_e32 v7, 1.0, v7
	v_rcp_f32_e32 v5, v5
	v_rcp_f32_e32 v6, v6
	v_rcp_f32_e32 v7, v7
	v_pk_mul_f32 v[0:1], v[0:1], v[4:5]
	s_nop 0
	v_and_b32_sdwa v4, v1, v196 dst_sel:DWORD dst_unused:UNUSED_PAD src0_sel:WORD_1 src1_sel:DWORD
	v_pk_mul_f32 v[6:7], v[8:9], v[6:7]
	v_and_b32_sdwa v5, v0, v196 dst_sel:DWORD dst_unused:UNUSED_PAD src0_sel:WORD_1 src1_sel:DWORD
	v_and_b32_sdwa v2, v7, v196 dst_sel:DWORD dst_unused:UNUSED_PAD src0_sel:WORD_1 src1_sel:DWORD
	v_and_b32_sdwa v3, v6, v196 dst_sel:DWORD dst_unused:UNUSED_PAD src0_sel:WORD_1 src1_sel:DWORD
	v_add3_u32 v1, v1, v4, s96
	v_add3_u32 v0, v0, v5, s96
	v_add3_u32 v3, v6, v3, s96
	v_add3_u32 v2, v7, v2, s96
	v_and_b32_e32 v1, 0xffff0000, v1
	v_and_b32_e32 v0, 0xffff0000, v0
	v_or_b32_sdwa v1, v1, v2 dst_sel:DWORD dst_unused:UNUSED_PAD src0_sel:DWORD src1_sel:WORD_1
	v_or_b32_sdwa v0, v0, v3 dst_sel:DWORD dst_unused:UNUSED_PAD src0_sel:DWORD src1_sel:WORD_1
	global_store_dwordx2 v[12:13], v[0:1], off offset:96
	s_branch .LBB0_788
